# static priority raise for the leading wave half (wr==0) during the GEMM epilogues, so its next-unit first load segment hides under the trailing half's epilogue tail
# baseline (speedup 1.0000x reference)
; #define PG8_BAR __builtin_amdgcn_s_barrier()
; template <class Epi, class Sched, bool ALIGN_EPI = false, bool SP2 = false>
; __device__ __forceinline__ void gemm_phase(PG8_LAS unsigned char* lds, const Gemm g, const Sched& S, const Epi& E) {
;     ...
;         if constexpr (ALIGN_EPI) { if (wr == 0) PG8_BAR; }
;         if constexpr (Epi::SPLIT) {
;             if (has_next) { E.first(acc, cur, rv1, wr, wc, fr, fq); prev = cur; }
;             else E(acc, cur, wr, wc, fr, fq, lds + STAGE_BYTES);
;         } else if constexpr (!Epi::AFTER_DRAIN) { E(acc, cur, wr, wc, fr, fq, lds + STAGE_BYTES); S.done(cur); }
.LBB0_263:
	s_and_b64 vcc, exec, s[18:19]
	s_cbranch_vccz .LBB0_265
	s_barrier
	s_setprio 1

; #define PG8_BAR __builtin_amdgcn_s_barrier()
; template <class Epi, class Sched, bool ALIGN_EPI = false, bool SP2 = false>
; __device__ __forceinline__ void gemm_phase(PG8_LAS unsigned char* lds, const Gemm g, const Sched& S, const Epi& E) {
;     ...
;         if constexpr (ALIGN_EPI) { if (wr == 0) PG8_BAR; }
;         if constexpr (Epi::SPLIT) {
;             if (has_next) { E.first(acc, cur, rv1, wr, wc, fr, fq); prev = cur; }
;             else E(acc, cur, wr, wc, fr, fq, lds + STAGE_BYTES);
;         } else if constexpr (!Epi::AFTER_DRAIN) { E(acc, cur, wr, wc, fr, fq, lds + STAGE_BYTES); S.done(cur); }
.LBB0_354:
	s_and_b64 vcc, exec, s[24:25]
	s_cbranch_vccz .LBB0_356
	s_barrier
	s_setprio 1

; #define PG8_BAR __builtin_amdgcn_s_barrier()
; template <class Epi, class Sched, bool ALIGN_EPI = false, bool SP2 = false>
; __device__ __forceinline__ void gemm_phase(PG8_LAS unsigned char* lds, const Gemm g, const Sched& S, const Epi& E) {
;     ...
;         if constexpr (ALIGN_EPI) { if (wr == 0) PG8_BAR; }
;         if constexpr (Epi::SPLIT) {
;             if (has_next) { E.first(acc, cur, rv1, wr, wc, fr, fq); prev = cur; }
;             else E(acc, cur, wr, wc, fr, fq, lds + STAGE_BYTES);
;         } else if constexpr (!Epi::AFTER_DRAIN) { E(acc, cur, wr, wc, fr, fq, lds + STAGE_BYTES); S.done(cur); }
.LBB0_465:
	s_and_b64 vcc, exec, s[20:21]
	s_cbranch_vccz .LBB0_467
	s_barrier
	s_setprio 1

; #define PG8_BAR __builtin_amdgcn_s_barrier()
; template <class Epi, class Sched, bool ALIGN_EPI = false, bool SP2 = false>
; __device__ __forceinline__ void gemm_phase(PG8_LAS unsigned char* lds, const Gemm g, const Sched& S, const Epi& E) {
;     ...
;         if constexpr (ALIGN_EPI) { if (wr == 0) PG8_BAR; }
;         if constexpr (Epi::SPLIT) {
;             if (has_next) { E.first(acc, cur, rv1, wr, wc, fr, fq); prev = cur; }
;             else E(acc, cur, wr, wc, fr, fq, lds + STAGE_BYTES);
;         } else if constexpr (!Epi::AFTER_DRAIN) { E(acc, cur, wr, wc, fr, fq, lds + STAGE_BYTES); S.done(cur); }
.LBB0_498:
	s_and_b64 vcc, exec, s[22:23]
	s_cbranch_vccz .LBB0_500
	s_barrier
	s_setprio 1
